# one static s_setprio 1 at kernel entry for the first-resident block of each CU (blocks 0..255); the partner block b+256 stays at priority 0
# baseline (speedup 1.0000x reference)
_Z8fwd_mega6Paramsii:
	s_mov_b32 s95, 0
	s_cmp_lt_u32 s2, 0x100
	s_cbranch_scc0 .Lprio_done
	s_setprio 1
.Lprio_done:
	s_load_dwordx2 s[52:53], s[0:1], 0x130
	s_add_u32 s6, s0, 0x130
	v_and_b32_e32 v168, 0x3ff, v0
	s_addc_u32 s7, s1, 0
	v_cmp_eq_u32_e64 s[4:5], 0, v168
	s_and_saveexec_b64 s[8:9], s[4:5]
	v_mov_b32_e32 v2, 0
	v_mov_b32_e32 v3, v2
	v_mov_b32_e32 v4, v2
	v_mov_b32_e32 v5, v2
	ds_write_b128 v2, v[2:5]
	s_or_b64 exec, exec, s[8:9]
	s_load_dword s78, s[0:1], 0x138
	s_load_dwordx2 s[46:47], s[0:1], 0x120
	s_waitcnt lgkmcnt(0)
	s_barrier
	s_getreg_b32 s3, hwreg(HW_REG_XCC_ID, 0, 4)
	s_and_b32 s33, s3, 15
	s_and_saveexec_b64 s[8:9], s[4:5]
	s_cbranch_execz .LBB0_5
	s_mov_b64 s[10:11], exec
	v_mbcnt_lo_u32_b32 v1, s10, 0
	v_mbcnt_hi_u32_b32 v1, s11, v1
	v_cmp_eq_u32_e32 vcc, 0, v1
	s_and_b64 s[12:13], exec, vcc
	s_mov_b64 exec, s[12:13]
	s_cbranch_execz .LBB0_5
	s_lshl_b32 s3, s33, 8
	s_bcnt1_i32_b64 s10, s[10:11]
	v_mov_b32_e32 v1, s3
	v_mov_b32_e32 v2, s10
	global_atomic_add v1, v2, s[46:47] offset:1024
